# P8 peeled first K-trip: first two counted waits allow the 8 epilogue stores to stay in flight (vmcnt 8 -> 16; same loads retired as in steady state); on top of v118
# speedup vs baseline: 1.0027x; 1.0027x over previous
;     __device__ bool next(int i, Unit& u) const { if (!so.next(i >> 1, u)) return false; u.sel = i & 1; return true; }
; #define PG8_STAGE(bufoff, gbase, voff) do { _Pragma("unroll") for (int _i = 0; _i < 2; ++_i) \
;         __builtin_amdgcn_global_load_lds((const unsigned*)((const char*)(gbase) + (voff)[_i]), (PG8_LAS unsigned*)(lds + (bufoff) + ldsw + _i * 8192), 16, 0, 0); } while (0)
; #define PG8_LDA(dst, b, h) do { _Pragma("unroll") for (int m = 0; m < 4; ++m) _Pragma("unroll") for (int k = 0; k < 2; ++k) dst[m][k] = *(const PG8_LAS bf16x8*)(lds + PG8_SA(b, h) + aoff + m * 2048 + k * 1024); } while (0)
; #define PG8_LDB(dst, b, h) do { _Pragma("unroll") for (int n = 0; n < 2; ++n) _Pragma("unroll") for (int k = 0; k < 2; ++k) dst[n][k] = *(const PG8_LAS bf16x8*)(lds + PG8_SB(b, h) + boff + n * 2048 + k * 1024); } while (0)
; #define PG8_WAIT_V(n) asm volatile("s_waitcnt vmcnt(" #n ")" ::: "memory")
; #define PG8_BAR __builtin_amdgcn_s_barrier()
; template <class Epi, class Sched, bool ALIGN_EPI = false, bool SP2 = false>
; __device__ __forceinline__ void gemm_phase(PG8_LAS unsigned char* lds, const Gemm g, const Sched& S, const Epi& E) {
;     ...
;         const bool has_next = S.next(ui + 1, nxt);
;         const char* nA = has_next ? (const char*)(nxt.sel ? g.A2 : g.A) + (size_t)nxt.pm * tstep : cA; const char* nB = has_next ? (const char*)(nxt.sel ? g.Bt2 : g.Bt) + (size_t)nxt.pn * tstep : cB;
;         for (int t = 0; t < nt; t += 2) {
;             const bool last = (t == nt - 2);
;             const char* a1 = cA + (size_t)(t + 1) * kstep;
;             const char* a2 = last ? nA : cA + (size_t)(t + 2) * kstep; const char* b2 = last ? nB : cB + (size_t)(t + 2) * kstep;
;             const char* a3 = a2 + kstep; const char* b3 = b2 + kstep;
;             if (last && has_next) S.a_ready(nxt);
;             if constexpr (SP2) {
;             PG8_LDB(B0, 0, 0); PG8_LDB(B1, 0, 1); PG8_SCHED; PG8_LDA(At, 0, 0); PG8_STAGE(PG8_SA(1, 1), a1 + hstep, voffA);
;             PG8_WAIT_V(8); PG8_WAIT_L(0); PG8_BAR; PG8_MMA(0, 0, At, B0); PG8_MMA(0, 1, At, B1); PG8_BAR; PG8_SCHED;
;             PG8_LDA(At, 0, 1); PG8_STAGE(PG8_SB(0, 0), b2, voffB); PG8_STAGE(PG8_SB(0, 1), b2 + hstep, voffB); PG8_STAGE(PG8_SA(0, 0), a2, voffA);
;             PG8_WAIT_V(8); PG8_WAIT_L(0); PG8_BAR; PG8_MMA(1, 0, At, B0); PG8_MMA(1, 1, At, B1); PG8_BAR; PG8_SCHED;
.Lcz_go_1021:
	s_add_u32 s42, s42, 0x80
	s_addc_u32 s43, s43, 0
	s_add_u32 s68, s44, 0x100
	s_addc_u32 s69, s45, 0
	s_mov_b32 s44, 0
	ds_read_b128 v[150:153], v147
	ds_read_b128 v[154:157], v147 offset:1024
	ds_read_b128 v[158:161], v147 offset:2048
	ds_read_b128 v[162:165], v147 offset:3072
	ds_read_b128 v[166:169], v148
	ds_read_b128 v[170:173], v148 offset:1024
	ds_read_b128 v[174:177], v148 offset:2048
	ds_read_b128 v[178:181], v148 offset:3072
	s_add_i32 s70, s44, 2
	s_add_u32 s16, s42, 0x80
	s_addc_u32 s17, s43, 0
	s_cmp_eq_u32 s58, s44
	s_cselect_b32 s44, s0, s16
	s_cselect_b32 s45, s1, s17
	s_cselect_b32 s73, s41, s69
	s_cselect_b32 s72, s40, s68
	v_lshl_add_u64 v[198:199], s[42:43], 0, v[136:137]
	s_add_i32 m0, s50, 0xc000
	ds_read_b128 v[182:185], v149
	ds_read_b128 v[186:189], v149 offset:1024
	ds_read_b128 v[190:193], v149 offset:2048
	ds_read_b128 v[194:197], v149 offset:3072
	ds_read_b128 v[202:205], v149 offset:4096
	ds_read_b128 v[206:209], v149 offset:5120
	ds_read_b128 v[210:213], v149 offset:6144
	ds_read_b128 v[214:217], v149 offset:7168
	global_load_lds_dwordx4 v[198:199], off
	v_lshl_add_u64 v[198:199], s[42:43], 0, v[138:139]
	s_add_i32 m0, s50, 0xe000
	s_nop 0
	global_load_lds_dwordx4 v[198:199], off
	s_waitcnt vmcnt(16)
	s_waitcnt lgkmcnt(0)
	s_barrier
	s_setprio 1
	s_waitcnt lgkmcnt(0)
	v_mfma_f32_16x16x32_bf16 v[124:127], v[150:153], v[182:185], 0
	v_mfma_f32_16x16x32_bf16 v[116:119], v[158:161], v[182:185], 0
	v_mfma_f32_16x16x32_bf16 v[108:111], v[150:153], v[190:193], 0
	v_mfma_f32_16x16x32_bf16 v[100:103], v[158:161], v[190:193], 0
	v_mfma_f32_16x16x32_bf16 v[92:95], v[150:153], v[202:205], 0
	v_mfma_f32_16x16x32_bf16 v[84:87], v[158:161], v[202:205], 0
	v_mfma_f32_16x16x32_bf16 v[76:79], v[150:153], v[210:213], 0
	v_mfma_f32_16x16x32_bf16 v[68:71], v[158:161], v[210:213], 0
	v_mfma_f32_16x16x32_bf16 v[124:127], v[154:157], v[186:189], v[124:127]
	v_mfma_f32_16x16x32_bf16 v[116:119], v[162:165], v[186:189], v[116:119]
	v_mfma_f32_16x16x32_bf16 v[108:111], v[154:157], v[194:197], v[108:111]
	v_mfma_f32_16x16x32_bf16 v[100:103], v[162:165], v[194:197], v[100:103]
	v_mfma_f32_16x16x32_bf16 v[92:95], v[154:157], v[206:209], v[92:95]
	v_mfma_f32_16x16x32_bf16 v[84:87], v[162:165], v[206:209], v[84:87]
	v_mfma_f32_16x16x32_bf16 v[76:79], v[154:157], v[214:217], v[76:79]
	v_mfma_f32_16x16x32_bf16 v[68:71], v[162:165], v[214:217], v[68:71]
	s_setprio 0
	s_setprio 1
	v_mfma_f32_16x16x32_bf16 v[120:123], v[166:169], v[182:185], 0
	v_mfma_f32_16x16x32_bf16 v[112:115], v[174:177], v[182:185], 0
	v_mfma_f32_16x16x32_bf16 v[104:107], v[166:169], v[190:193], 0
	v_mfma_f32_16x16x32_bf16 v[96:99], v[174:177], v[190:193], 0
	v_mfma_f32_16x16x32_bf16 v[88:91], v[166:169], v[202:205], 0
	v_mfma_f32_16x16x32_bf16 v[80:83], v[174:177], v[202:205], 0
	v_mfma_f32_16x16x32_bf16 v[72:75], v[166:169], v[210:213], 0
	v_mfma_f32_16x16x32_bf16 v[64:67], v[174:177], v[210:213], 0
	v_mfma_f32_16x16x32_bf16 v[120:123], v[170:173], v[186:189], v[120:123]
	v_mfma_f32_16x16x32_bf16 v[112:115], v[178:181], v[186:189], v[112:115]
	v_mfma_f32_16x16x32_bf16 v[104:107], v[170:173], v[194:197], v[104:107]
	v_mfma_f32_16x16x32_bf16 v[96:99], v[178:181], v[194:197], v[96:99]
	v_mfma_f32_16x16x32_bf16 v[88:91], v[170:173], v[206:209], v[88:91]
	v_mfma_f32_16x16x32_bf16 v[80:83], v[178:181], v[206:209], v[80:83]
	v_mfma_f32_16x16x32_bf16 v[72:75], v[170:173], v[214:217], v[72:75]
	v_mfma_f32_16x16x32_bf16 v[64:67], v[178:181], v[214:217], v[64:67]
	s_setprio 0
	s_barrier
	s_add_i32 s16, s61, s47
	v_lshl_add_u64 v[198:199], s[72:73], 0, v[132:133]
	s_mov_b32 m0, s16
	ds_read_b128 v[182:185], v149 offset:16384
	ds_read_b128 v[186:189], v149 offset:17408
	ds_read_b128 v[190:193], v149 offset:18432
	ds_read_b128 v[194:197], v149 offset:19456
	ds_read_b128 v[202:205], v149 offset:20480
	ds_read_b128 v[206:209], v149 offset:21504
	ds_read_b128 v[210:213], v149 offset:22528
	ds_read_b128 v[214:217], v149 offset:23552
	global_load_lds_dwordx4 v[198:199], off
	s_add_i32 m0, s16, 0x2000
	v_lshl_add_u64 v[218:219], s[72:73], 0, v[128:129]
	s_add_u32 s72, s72, s10
	s_addc_u32 s73, s73, s11
	s_add_i32 s16, s62, s47
	global_load_lds_dwordx4 v[218:219], off
	v_lshl_add_u64 v[220:221], s[72:73], 0, v[132:133]
	s_mov_b32 m0, s16
	v_lshl_add_u64 v[222:223], s[72:73], 0, v[128:129]
	global_load_lds_dwordx4 v[220:221], off
	s_add_i32 m0, s16, 0x2000
	v_lshl_add_u64 v[224:225], s[44:45], 0, v[134:135]
	global_load_lds_dwordx4 v[222:223], off
	s_mov_b32 m0, s50
	v_lshl_add_u64 v[226:227], s[44:45], 0, v[130:131]
	global_load_lds_dwordx4 v[224:225], off
	s_mov_b32 m0, s51
	s_nop 0
	global_load_lds_dwordx4 v[226:227], off
	s_waitcnt vmcnt(16)
	s_waitcnt lgkmcnt(0)
	s_barrier
; #define PG8_STAGE(bufoff, gbase, voff) do { _Pragma("unroll") for (int _i = 0; _i < 2; ++_i) \
;         __builtin_amdgcn_global_load_lds((const unsigned*)((const char*)(gbase) + (voff)[_i]), (PG8_LAS unsigned*)(lds + (bufoff) + ldsw + _i * 8192), 16, 0, 0); } while (0)
; #define PG8_LDA(dst, b, h) do { _Pragma("unroll") for (int m = 0; m < 4; ++m) _Pragma("unroll") for (int k = 0; k < 2; ++k) dst[m][k] = *(const PG8_LAS bf16x8*)(lds + PG8_SA(b, h) + aoff + m * 2048 + k * 1024); } while (0)
; #define PG8_LDB(dst, b, h) do { _Pragma("unroll") for (int n = 0; n < 2; ++n) _Pragma("unroll") for (int k = 0; k < 2; ++k) dst[n][k] = *(const PG8_LAS bf16x8*)(lds + PG8_SB(b, h) + boff + n * 2048 + k * 1024); } while (0)
; #define PG8_MMA(ai, bj, At, Bt) do { __builtin_amdgcn_s_setprio(1); _Pragma("unroll") for (int m = 0; m < 4; ++m) _Pragma("unroll") for (int n = 0; n < 2; ++n) _Pragma("unroll") for (int k = 0; k < 2; ++k) \
;         acc[ai][bj][m][n] = __builtin_amdgcn_mfma_f32_16x16x32_bf16(Bt[n][k], At[m][k], acc[ai][bj][m][n], 0, 0, 0); __builtin_amdgcn_s_setprio(0); } while (0)
; #define PG8_WAIT_V(n) asm volatile("s_waitcnt vmcnt(" #n ")" ::: "memory")
; #define PG8_WAIT_L(n) asm volatile("s_waitcnt lgkmcnt(" #n ")" ::: "memory")
; #define PG8_BAR __builtin_amdgcn_s_barrier()
; #define PG8_SCHED __builtin_amdgcn_sched_barrier(0)
; template <class Epi, class Sched, bool ALIGN_EPI = false, bool SP2 = false>
; __device__ __forceinline__ void gemm_phase(PG8_LAS unsigned char* lds, const Gemm g, const Sched& S, const Epi& E) {
;     ...
;             PG8_WAIT_V(8); PG8_WAIT_L(0); PG8_BAR; PG8_MMA(1, 0, At, B0); PG8_MMA(1, 1, At, B1); PG8_BAR; PG8_SCHED;
;             PG8_LDB(B0, 1, 0); PG8_LDB(B1, 1, 1); PG8_SCHED; PG8_LDA(At, 1, 0); PG8_STAGE(PG8_SA(0, 1), a2 + hstep, voffA);
;             PG8_WAIT_V(8); PG8_WAIT_L(0); PG8_BAR; PG8_MMA(0, 0, At, B0); PG8_MMA(0, 1, At, B1); PG8_BAR; PG8_SCHED;
;             PG8_LDA(At, 1, 1); PG8_STAGE(PG8_SB(1, 0), b3, voffB); PG8_STAGE(PG8_SB(1, 1), b3 + hstep, voffB); PG8_STAGE(PG8_SA(1, 0), a3, voffA);
	s_setprio 1
	s_waitcnt lgkmcnt(0)
	v_mfma_f32_16x16x32_bf16 v[60:63], v[150:153], v[182:185], 0
	v_mfma_f32_16x16x32_bf16 v[52:55], v[158:161], v[182:185], 0
	v_mfma_f32_16x16x32_bf16 v[44:47], v[150:153], v[190:193], 0
	v_mfma_f32_16x16x32_bf16 v[36:39], v[158:161], v[190:193], 0
	v_mfma_f32_16x16x32_bf16 v[28:31], v[150:153], v[202:205], 0
	v_mfma_f32_16x16x32_bf16 v[20:23], v[158:161], v[202:205], 0
	v_mfma_f32_16x16x32_bf16 v[12:15], v[150:153], v[210:213], 0
	v_mfma_f32_16x16x32_bf16 v[4:7], v[158:161], v[210:213], 0
	v_mfma_f32_16x16x32_bf16 v[60:63], v[154:157], v[186:189], v[60:63]
	v_mfma_f32_16x16x32_bf16 v[52:55], v[162:165], v[186:189], v[52:55]
	v_mfma_f32_16x16x32_bf16 v[44:47], v[154:157], v[194:197], v[44:47]
	v_mfma_f32_16x16x32_bf16 v[36:39], v[162:165], v[194:197], v[36:39]
	v_mfma_f32_16x16x32_bf16 v[28:31], v[154:157], v[206:209], v[28:31]
	v_mfma_f32_16x16x32_bf16 v[20:23], v[162:165], v[206:209], v[20:23]
	v_mfma_f32_16x16x32_bf16 v[12:15], v[154:157], v[214:217], v[12:15]
	v_mfma_f32_16x16x32_bf16 v[4:7], v[162:165], v[214:217], v[4:7]
	s_setprio 0
	s_setprio 1
	v_mfma_f32_16x16x32_bf16 v[56:59], v[166:169], v[182:185], 0
	v_mfma_f32_16x16x32_bf16 v[48:51], v[174:177], v[182:185], 0
	v_mfma_f32_16x16x32_bf16 v[40:43], v[166:169], v[190:193], 0
	v_mfma_f32_16x16x32_bf16 v[32:35], v[174:177], v[190:193], 0
	v_mfma_f32_16x16x32_bf16 v[24:27], v[166:169], v[202:205], 0
	v_mfma_f32_16x16x32_bf16 v[16:19], v[174:177], v[202:205], 0
	v_mfma_f32_16x16x32_bf16 v[8:11], v[166:169], v[210:213], 0
	v_mfma_f32_16x16x32_bf16 v[0:3], v[174:177], v[210:213], 0
	v_mfma_f32_16x16x32_bf16 v[56:59], v[170:173], v[186:189], v[56:59]
	v_mfma_f32_16x16x32_bf16 v[48:51], v[178:181], v[186:189], v[48:51]
	v_mfma_f32_16x16x32_bf16 v[40:43], v[170:173], v[194:197], v[40:43]
	v_mfma_f32_16x16x32_bf16 v[32:35], v[178:181], v[194:197], v[32:35]
	v_mfma_f32_16x16x32_bf16 v[24:27], v[170:173], v[206:209], v[24:27]
	v_mfma_f32_16x16x32_bf16 v[16:19], v[178:181], v[206:209], v[16:19]
	v_mfma_f32_16x16x32_bf16 v[8:11], v[170:173], v[214:217], v[8:11]
	v_mfma_f32_16x16x32_bf16 v[0:3], v[178:181], v[214:217], v[0:3]
	s_setprio 0
	s_barrier
	s_add_i32 s16, 0, 0x18000
	s_add_i32 s17, 0, 0x1c000
	v_add_u32_e32 v162, s16, v145
	v_add_u32_e32 v178, s17, v145
	ds_read_b128 v[150:153], v162
	ds_read_b128 v[154:157], v162 offset:1024
	ds_read_b128 v[158:161], v162 offset:2048
	ds_read_b128 v[162:165], v162 offset:3072
	ds_read_b128 v[166:169], v178
	ds_read_b128 v[170:173], v178 offset:1024
	ds_read_b128 v[174:177], v178 offset:2048
	ds_read_b128 v[178:181], v178 offset:3072
	s_add_u32 s44, s44, s10
	s_addc_u32 s45, s45, s11
	s_mov_b32 m0, s52
	v_lshl_add_u64 v[228:229], s[44:45], 0, v[134:135]
	ds_read_b128 v[182:185], v149 offset:32768
	ds_read_b128 v[186:189], v149 offset:33792
	ds_read_b128 v[190:193], v149 offset:34816
	ds_read_b128 v[194:197], v149 offset:35840
	ds_read_b128 v[202:205], v149 offset:36864
	ds_read_b128 v[206:209], v149 offset:37888
	ds_read_b128 v[210:213], v149 offset:38912
	ds_read_b128 v[214:217], v149 offset:39936
	global_load_lds_dwordx4 v[228:229], off
	v_lshl_add_u64 v[228:229], s[44:45], 0, v[130:131]
	s_mov_b32 m0, s53
	s_nop 0
	global_load_lds_dwordx4 v[228:229], off
	s_waitcnt vmcnt(8)
	s_waitcnt lgkmcnt(0)
	s_barrier
	s_setprio 1
	s_waitcnt lgkmcnt(0)
	v_mfma_f32_16x16x32_bf16 v[124:127], v[150:153], v[182:185], v[124:127]
	v_mfma_f32_16x16x32_bf16 v[116:119], v[158:161], v[182:185], v[116:119]
	v_mfma_f32_16x16x32_bf16 v[108:111], v[150:153], v[190:193], v[108:111]
	v_mfma_f32_16x16x32_bf16 v[100:103], v[158:161], v[190:193], v[100:103]
	v_mfma_f32_16x16x32_bf16 v[92:95], v[150:153], v[202:205], v[92:95]
	v_mfma_f32_16x16x32_bf16 v[84:87], v[158:161], v[202:205], v[84:87]
	v_mfma_f32_16x16x32_bf16 v[76:79], v[150:153], v[210:213], v[76:79]
	v_mfma_f32_16x16x32_bf16 v[68:71], v[158:161], v[210:213], v[68:71]
	v_mfma_f32_16x16x32_bf16 v[124:127], v[154:157], v[186:189], v[124:127]
	v_mfma_f32_16x16x32_bf16 v[116:119], v[162:165], v[186:189], v[116:119]
	v_mfma_f32_16x16x32_bf16 v[108:111], v[154:157], v[194:197], v[108:111]
	v_mfma_f32_16x16x32_bf16 v[100:103], v[162:165], v[194:197], v[100:103]
	v_mfma_f32_16x16x32_bf16 v[92:95], v[154:157], v[206:209], v[92:95]
	v_mfma_f32_16x16x32_bf16 v[84:87], v[162:165], v[206:209], v[84:87]
	v_mfma_f32_16x16x32_bf16 v[76:79], v[154:157], v[214:217], v[76:79]
	v_mfma_f32_16x16x32_bf16 v[68:71], v[162:165], v[214:217], v[68:71]
	s_setprio 0
	s_setprio 1
	v_mfma_f32_16x16x32_bf16 v[120:123], v[166:169], v[182:185], v[120:123]
	v_mfma_f32_16x16x32_bf16 v[112:115], v[174:177], v[182:185], v[112:115]
	v_mfma_f32_16x16x32_bf16 v[104:107], v[166:169], v[190:193], v[104:107]
	v_mfma_f32_16x16x32_bf16 v[96:99], v[174:177], v[190:193], v[96:99]
	v_mfma_f32_16x16x32_bf16 v[88:91], v[166:169], v[202:205], v[88:91]
	v_mfma_f32_16x16x32_bf16 v[80:83], v[174:177], v[202:205], v[80:83]
	v_mfma_f32_16x16x32_bf16 v[72:75], v[166:169], v[210:213], v[72:75]
	v_mfma_f32_16x16x32_bf16 v[64:67], v[174:177], v[210:213], v[64:67]
	v_mfma_f32_16x16x32_bf16 v[120:123], v[170:173], v[186:189], v[120:123]
	v_mfma_f32_16x16x32_bf16 v[112:115], v[178:181], v[186:189], v[112:115]
	v_mfma_f32_16x16x32_bf16 v[104:107], v[170:173], v[194:197], v[104:107]
	v_mfma_f32_16x16x32_bf16 v[96:99], v[178:181], v[194:197], v[96:99]
	v_mfma_f32_16x16x32_bf16 v[88:91], v[170:173], v[206:209], v[88:91]
	v_mfma_f32_16x16x32_bf16 v[80:83], v[178:181], v[206:209], v[80:83]
	v_mfma_f32_16x16x32_bf16 v[72:75], v[170:173], v[214:217], v[72:75]
	v_mfma_f32_16x16x32_bf16 v[64:67], v[178:181], v[214:217], v[64:67]
	s_setprio 0
	s_barrier
; #define PG8_STAGE(bufoff, gbase, voff) do { _Pragma("unroll") for (int _i = 0; _i < 2; ++_i) \
;         __builtin_amdgcn_global_load_lds((const unsigned*)((const char*)(gbase) + (voff)[_i]), (PG8_LAS unsigned*)(lds + (bufoff) + ldsw + _i * 8192), 16, 0, 0); } while (0)
; #define PG8_LDA(dst, b, h) do { _Pragma("unroll") for (int m = 0; m < 4; ++m) _Pragma("unroll") for (int k = 0; k < 2; ++k) dst[m][k] = *(const PG8_LAS bf16x8*)(lds + PG8_SA(b, h) + aoff + m * 2048 + k * 1024); } while (0)
; #define PG8_MMA(ai, bj, At, Bt) do { __builtin_amdgcn_s_setprio(1); _Pragma("unroll") for (int m = 0; m < 4; ++m) _Pragma("unroll") for (int n = 0; n < 2; ++n) _Pragma("unroll") for (int k = 0; k < 2; ++k) \
;         acc[ai][bj][m][n] = __builtin_amdgcn_mfma_f32_16x16x32_bf16(Bt[n][k], At[m][k], acc[ai][bj][m][n], 0, 0, 0); __builtin_amdgcn_s_setprio(0); } while (0)
; #define PG8_WAIT_V(n) asm volatile("s_waitcnt vmcnt(" #n ")" ::: "memory")
; #define PG8_WAIT_L(n) asm volatile("s_waitcnt lgkmcnt(" #n ")" ::: "memory")
; #define PG8_BAR __builtin_amdgcn_s_barrier()
; #define PG8_SCHED __builtin_amdgcn_sched_barrier(0)
; template <class Epi, class Sched, bool ALIGN_EPI = false, bool SP2 = false>
; __device__ __forceinline__ void gemm_phase(PG8_LAS unsigned char* lds, const Gemm g, const Sched& S, const Epi& E) {
;     ...
;         for (int t = 0; t < nt; t += 2) {
;             const bool last = (t == nt - 2);
;     ...
;             PG8_LDA(At, 1, 1); PG8_STAGE(PG8_SB(1, 0), b3, voffB); PG8_STAGE(PG8_SB(1, 1), b3 + hstep, voffB); PG8_STAGE(PG8_SA(1, 0), a3, voffA);
;             PG8_WAIT_V(8); PG8_WAIT_L(0); PG8_BAR; PG8_MMA(1, 0, At, B0); PG8_MMA(1, 1, At, B1); PG8_BAR; PG8_SCHED;
	s_add_i32 s16, s16, s47
	v_lshl_add_u64 v[198:199], v[198:199], 0, s[36:37]
	s_mov_b32 m0, s16
	ds_read_b128 v[182:185], v149 offset:49152
	ds_read_b128 v[186:189], v149 offset:50176
	ds_read_b128 v[190:193], v149 offset:51200
	ds_read_b128 v[194:197], v149 offset:52224
	ds_read_b128 v[202:205], v149 offset:53248
	ds_read_b128 v[206:209], v149 offset:54272
	ds_read_b128 v[210:213], v149 offset:55296
	ds_read_b128 v[214:217], v149 offset:56320
	global_load_lds_dwordx4 v[198:199], off
	v_lshl_add_u64 v[198:199], v[218:219], 0, s[36:37]
	s_add_i32 m0, s16, 0x2000
	s_add_i32 s16, s17, s47
	global_load_lds_dwordx4 v[198:199], off
	v_lshl_add_u64 v[198:199], v[220:221], 0, s[36:37]
	s_mov_b32 m0, s16
	s_nop 0
	global_load_lds_dwordx4 v[198:199], off
	v_lshl_add_u64 v[198:199], v[222:223], 0, s[36:37]
	s_add_i32 m0, s16, 0x2000
	s_nop 0
	global_load_lds_dwordx4 v[198:199], off
	v_lshl_add_u64 v[198:199], v[224:225], 0, s[36:37]
	s_mov_b32 m0, s55
	s_nop 0
	global_load_lds_dwordx4 v[198:199], off
	v_lshl_add_u64 v[198:199], v[226:227], 0, s[36:37]
	s_mov_b32 m0, s56
	s_nop 0
	global_load_lds_dwordx4 v[198:199], off
	s_waitcnt vmcnt(8)
	s_waitcnt lgkmcnt(0)
	s_barrier
	s_setprio 1
	s_waitcnt lgkmcnt(0)
	v_mfma_f32_16x16x32_bf16 v[60:63], v[150:153], v[182:185], v[60:63]
	v_mfma_f32_16x16x32_bf16 v[52:55], v[158:161], v[182:185], v[52:55]
	v_mfma_f32_16x16x32_bf16 v[44:47], v[150:153], v[190:193], v[44:47]
	v_mfma_f32_16x16x32_bf16 v[36:39], v[158:161], v[190:193], v[36:39]
	v_mfma_f32_16x16x32_bf16 v[28:31], v[150:153], v[202:205], v[28:31]
	v_mfma_f32_16x16x32_bf16 v[20:23], v[158:161], v[202:205], v[20:23]
	v_mfma_f32_16x16x32_bf16 v[12:15], v[150:153], v[210:213], v[12:15]
	v_mfma_f32_16x16x32_bf16 v[4:7], v[158:161], v[210:213], v[4:7]
	v_mfma_f32_16x16x32_bf16 v[60:63], v[154:157], v[186:189], v[60:63]
	v_mfma_f32_16x16x32_bf16 v[52:55], v[162:165], v[186:189], v[52:55]
	v_mfma_f32_16x16x32_bf16 v[44:47], v[154:157], v[194:197], v[44:47]
	v_mfma_f32_16x16x32_bf16 v[36:39], v[162:165], v[194:197], v[36:39]
	v_mfma_f32_16x16x32_bf16 v[28:31], v[154:157], v[206:209], v[28:31]
	v_mfma_f32_16x16x32_bf16 v[20:23], v[162:165], v[206:209], v[20:23]
	v_mfma_f32_16x16x32_bf16 v[12:15], v[154:157], v[214:217], v[12:15]
	v_mfma_f32_16x16x32_bf16 v[4:7], v[162:165], v[214:217], v[4:7]
	s_setprio 0
	s_setprio 1
	v_mfma_f32_16x16x32_bf16 v[56:59], v[166:169], v[182:185], v[56:59]
	v_mfma_f32_16x16x32_bf16 v[48:51], v[174:177], v[182:185], v[48:51]
	v_mfma_f32_16x16x32_bf16 v[40:43], v[166:169], v[190:193], v[40:43]
	v_mfma_f32_16x16x32_bf16 v[32:35], v[174:177], v[190:193], v[32:35]
	v_mfma_f32_16x16x32_bf16 v[24:27], v[166:169], v[202:205], v[24:27]
	v_mfma_f32_16x16x32_bf16 v[16:19], v[174:177], v[202:205], v[16:19]
	v_mfma_f32_16x16x32_bf16 v[8:11], v[166:169], v[210:213], v[8:11]
	v_mfma_f32_16x16x32_bf16 v[0:3], v[174:177], v[210:213], v[0:3]
	v_mfma_f32_16x16x32_bf16 v[56:59], v[170:173], v[186:189], v[56:59]
	v_mfma_f32_16x16x32_bf16 v[48:51], v[178:181], v[186:189], v[48:51]
	v_mfma_f32_16x16x32_bf16 v[40:43], v[170:173], v[194:197], v[40:43]
	v_mfma_f32_16x16x32_bf16 v[32:35], v[178:181], v[194:197], v[32:35]
	v_mfma_f32_16x16x32_bf16 v[24:27], v[170:173], v[206:209], v[24:27]
	v_mfma_f32_16x16x32_bf16 v[16:19], v[178:181], v[206:209], v[16:19]
	v_mfma_f32_16x16x32_bf16 v[8:11], v[170:173], v[214:217], v[8:11]
	v_mfma_f32_16x16x32_bf16 v[0:3], v[178:181], v[214:217], v[0:3]
	s_setprio 0
	s_barrier
	s_add_u32 s42, s42, 0x100
	s_addc_u32 s43, s43, 0
	s_add_u32 s68, s68, 0x100
	s_addc_u32 s69, s69, 0
	s_cmp_ge_i32 s70, s57
	s_mov_b32 s44, s70
	s_cbranch_scc1 .LBB0_1022
